# v57 + MLA loop: static s_setprio 1 for waves 4-7 (reset at loop exit)
# baseline (speedup 1.0000x reference)
.LBB0_542:
	v_cndmask_b32_e64 v202, v50, v1, s[2:3]
	v_mul_f32_e32 v50, 0xbdd53b94, v202
	v_fmamk_f32 v35, v35, 0x3dd53b94, v50
	v_fmamk_f32 v34, v34, 0x3dd53b94, v50
	v_fmamk_f32 v36, v36, 0x3dd53b94, v50
	v_exp_f32_e32 v231, v35
	v_lshlrev_b32_e32 v35, 4, v161
	v_exp_f32_e32 v229, v34
	v_exp_f32_e32 v227, v36
	v_lshlrev_b32_e32 v34, 3, v161
	v_and_b32_e32 v35, 0xc0, v35
	v_lshlrev_b32_e32 v36, 1, v161
	v_and_or_b32 v35, v34, 24, v35
	v_and_b32_e32 v36, 32, v36
	v_and_b32_e32 v34, 0x100, v34
	s_cmp_lg_u32 0, -1
	v_fmamk_f32 v37, v37, 0x3dd53b94, v50
	v_fmamk_f32 v38, v38, 0x3dd53b94, v50
	v_fmamk_f32 v39, v39, 0x3dd53b94, v50
	v_fmamk_f32 v40, v40, 0x3dd53b94, v50
	v_fmamk_f32 v41, v41, 0x3dd53b94, v50
	v_fmamk_f32 v42, v42, 0x3dd53b94, v50
	v_fmamk_f32 v43, v43, 0x3dd53b94, v50
	v_fmamk_f32 v44, v44, 0x3dd53b94, v50
	v_fmamk_f32 v45, v45, 0x3dd53b94, v50
	v_fmamk_f32 v46, v46, 0x3dd53b94, v50
	v_fmamk_f32 v47, v47, 0x3dd53b94, v50
	v_fmamk_f32 v48, v48, 0x3dd53b94, v50
	v_fmamk_f32 v49, v49, 0x3dd53b94, v50
	v_or3_b32 v34, v35, v36, v34
	s_cselect_b32 s1, 0, 0
	v_exp_f32_e32 v230, v37
	v_exp_f32_e32 v226, v38
	v_exp_f32_e32 v228, v39
	v_exp_f32_e32 v224, v40
	v_exp_f32_e32 v225, v41
	v_exp_f32_e32 v221, v42
	v_exp_f32_e32 v223, v43
	v_exp_f32_e32 v220, v44
	v_exp_f32_e32 v222, v45
	v_exp_f32_e32 v217, v46
	v_exp_f32_e32 v219, v47
	v_exp_f32_e32 v216, v48
	v_exp_f32_e32 v218, v49
	v_add_u32_e32 v200, s1, v34
	s_and_b32 s1, s84, 7
	s_lshl_b32 s1, s1, 9
	s_waitcnt vmcnt(0)
	v_pk_fma_f32 v[146:147], v[32:33], s[34:35], v[50:51] op_sel_hi:[1,0,0]
	v_pk_fma_f32 v[148:149], v[30:31], s[34:35], v[50:51] op_sel_hi:[1,0,0]
	v_pk_fma_f32 v[150:151], v[28:29], s[34:35], v[50:51] op_sel_hi:[1,0,0]
	v_pk_fma_f32 v[152:153], v[26:27], s[34:35], v[50:51] op_sel_hi:[1,0,0]
	v_pk_fma_f32 v[154:155], v[24:25], s[34:35], v[50:51] op_sel_hi:[1,0,0]
	v_pk_fma_f32 v[156:157], v[22:23], s[34:35], v[50:51] op_sel_hi:[1,0,0]
	v_pk_fma_f32 v[162:163], v[20:21], s[34:35], v[50:51] op_sel_hi:[1,0,0]
	v_pk_fma_f32 v[164:165], v[18:19], s[34:35], v[50:51] op_sel_hi:[1,0,0]
	v_lshl_add_u32 v170, v168, 2, v51
	v_lshl_add_u32 v158, v52, 2, v51
	s_add_u32 s20, s4, s1
	v_mov_b64_e32 v[64:65], v[16:17]
	v_mov_b64_e32 v[48:49], v[16:17]
	v_mov_b64_e32 v[32:33], v[16:17]
	s_mov_b32 s17, 1
	s_mov_b32 s0, 0
	v_cmp_gt_u32_e64 s[2:3], 32, v161
	s_mov_b32 s19, 2
	s_addc_u32 s21, s5, 0
	v_mov_b32_e32 v171, 0
	v_mov_b64_e32 v[62:63], v[14:15]
	v_mov_b64_e32 v[60:61], v[12:13]
	v_mov_b64_e32 v[58:59], v[10:11]
	v_mov_b64_e32 v[56:57], v[8:9]
	v_mov_b64_e32 v[54:55], v[6:7]
	v_mov_b64_e32 v[52:53], v[4:5]
	v_mov_b64_e32 v[50:51], v[2:3]
	v_mov_b64_e32 v[46:47], v[14:15]
	v_mov_b64_e32 v[44:45], v[12:13]
	v_mov_b64_e32 v[42:43], v[10:11]
	v_mov_b64_e32 v[40:41], v[8:9]
	v_mov_b64_e32 v[38:39], v[6:7]
	v_mov_b64_e32 v[36:37], v[4:5]
	v_mov_b64_e32 v[34:35], v[2:3]
	v_mov_b64_e32 v[30:31], v[14:15]
	v_mov_b64_e32 v[28:29], v[12:13]
	v_mov_b64_e32 v[26:27], v[10:11]
	v_mov_b64_e32 v[24:25], v[8:9]
	v_mov_b64_e32 v[22:23], v[6:7]
	v_mov_b64_e32 v[20:21], v[4:5]
	v_mov_b64_e32 v[18:19], v[2:3]
	s_mov_b32 s22, 2
	s_waitcnt vmcnt(0)
	s_barrier
	v_mov_b32_e32 v245, v172
	v_ashrrev_i32_e32 v250, 4, v245
	v_xor_b32_e32 v246, v250, v245
	v_lshlrev_b32_e32 v246, 3, v246
	v_lshrrev_b32_e32 v247, 1, v245
	v_and_b32_e32 v246, 0x78, v246
	v_and_b32_e32 v255, 8, v247
	v_lshrrev_b32_e32 v247, 1, v250
	v_bfe_u32 v254, v245, 2, 2
	v_and_b32_e32 v248, 4, v247
	v_lshl_or_b32 v246, v250, 11, v246
	v_and_or_b32 v250, v250, s75, v255
	v_lshlrev_b32_e32 v247, 3, v245
	v_or3_b32 v250, v250, v248, v254
	v_and_b32_e32 v251, 0x60, v245
	v_and_b32_e32 v249, 24, v247
	v_lshlrev_b32_e32 v250, 11, v250
	v_or3_b32 v250, v250, v251, v249
	v_ashrrev_i32_e32 v247, 31, v246
	v_ashrrev_i32_e32 v251, 31, v250
	v_lshlrev_b64 v[246:247], 1, v[246:247]
	v_lshlrev_b64 v[248:249], 1, v[250:251]
	v_lshrrev_b32_e32 v255, 4, v245
	v_lshrrev_b32_e32 v254, 3, v245
	v_xor_b32_e32 v255, v255, v245
	v_mul_lo_u32 v254, v254, s76
	v_lshlrev_b32_e32 v255, 3, v255
	v_and_or_b32 v254, v255, 56, v254
	v_ashrrev_i32_e32 v255, 31, v254
	v_lshlrev_b64 v[250:251], 1, v[254:255]
	v_readfirstlane_b32 s99, v184
	s_nop 3
	s_cmpk_lt_u32 s99, 0x100
	s_cbranch_scc1 .Lmla_noprio
	s_setprio 1
.Lmla_noprio:
	s_mov_b32 s23, s17
	s_mov_b32 s17, s0
	s_add_i32 s71, 0, 0x10000
	ds_read_b128 v[66:69], v174 offset:49152
	ds_read_b128 v[70:73], v174 offset:57344
	ds_read_b128 v[206:209], v176 offset:49152
	ds_read_b128 v[210:213], v176 offset:57344
	s_waitcnt lgkmcnt(0)
	v_mfma_f32_32x32x16_bf16 v[82:97], v[66:69], v[142:145], 0
	s_add_i32 s0, 0, 0x16000
	v_exp_f32_e32 v240, v146
	v_add_f32_e32 v146, 0, v229
	v_add_f32_e32 v146, v231, v146
	v_add_f32_e32 v146, v227, v146
	v_add_f32_e32 v146, v230, v146
	v_add_f32_e32 v146, v226, v146
	v_mfma_f32_32x32x16_bf16 v[66:81], v[70:73], v[142:145], 0
	v_add_f32_e32 v146, v228, v146
	v_add_f32_e32 v146, v224, v146
	v_add_f32_e32 v146, v225, v146
	v_add_f32_e32 v146, v221, v146
	v_add_f32_e32 v146, v223, v146
	v_add_f32_e32 v146, v220, v146
	v_add_f32_e32 v146, v222, v146
	v_mfma_f32_32x32x16_bf16 v[82:97], v[206:209], v[138:141], v[82:97]
	v_exp_f32_e32 v164, v164
	v_add_f32_e32 v146, v217, v146
	v_exp_f32_e32 v165, v165
	v_add_f32_e32 v146, v219, v146
	v_exp_f32_e32 v197, v162
	v_add_f32_e32 v146, v216, v146
	v_add_f32_e32 v146, v218, v146
	v_mfma_f32_32x32x16_bf16 v[66:81], v[210:213], v[138:141], v[66:81]
	ds_read_b128 v[206:209], v178 offset:49152
	ds_read_b128 v[210:213], v178 offset:57344
	s_add_u32 s4, s38, s20
	s_addc_u32 s5, s39, s21
	s_add_u32 s24, s4, 0x149ec400
	s_addc_u32 s25, s5, 0
	s_mov_b32 m0, s90
	v_lshl_add_u64 v[254:255], v[246:247], 0, s[24:25]
	s_lshl_b32 s18, s22, 14
	global_load_lds_dwordx4 v[254:255], off
	s_add_u32 s24, s4, 0x14a0c400
	s_addc_u32 s25, s5, 0
	s_mov_b32 m0, s91
	v_lshl_add_u64 v[254:255], v[246:247], 0, s[24:25]
	s_add_i32 s1, s89, s18
	global_load_lds_dwordx4 v[254:255], off
	s_add_u32 s24, s4, 0x149ec500
	s_addc_u32 s25, s5, 0
	s_mov_b32 m0, s1
	v_lshl_add_u64 v[254:255], v[248:249], 0, s[24:25]
	global_load_lds_dwordx4 v[254:255], off
	s_add_u32 s24, s4, 0x14a0c500
	s_addc_u32 s25, s5, 0
	s_add_i32 m0, s1, 0x2000
	v_lshl_add_u64 v[254:255], v[248:249], 0, s[24:25]
	global_load_lds_dwordx4 v[254:255], off
	s_add_u32 s4, s38, s88
	s_addc_u32 s5, s39, s87
	s_add_u32 s4, s4, s36
	s_addc_u32 s5, s5, s37
	s_mov_b32 m0, s92
	v_lshl_add_u64 v[254:255], v[250:251], 0, s[4:5]
	global_load_lds_dwordx4 v[254:255], off
	v_exp_f32_e32 v156, v156
	v_add_f32_e32 v146, v164, v146
	v_exp_f32_e32 v157, v157
	v_add_f32_e32 v146, v165, v146
	v_add_f32_e32 v146, v197, v146
	v_exp_f32_e32 v241, v147
	s_waitcnt lgkmcnt(0)
	v_mfma_f32_32x32x16_bf16 v[82:97], v[206:209], v[134:137], v[82:97]
	v_mfma_f32_32x32x16_bf16 v[66:81], v[210:213], v[134:137], v[66:81]
	ds_read_b128 v[208:211], v180 offset:49152
	ds_read_b128 v[212:215], v180 offset:57344
	s_waitcnt lgkmcnt(0)
	v_mfma_f32_32x32x16_bf16 v[82:97], v[208:211], v[130:133], v[82:97]
	v_mfma_f32_32x32x16_bf16 v[66:81], v[212:215], v[130:133], v[66:81]
	ds_read_b128 v[208:211], v182 offset:49152
	ds_read_b128 v[212:215], v182 offset:57344
	s_waitcnt lgkmcnt(0)
	v_mfma_f32_32x32x16_bf16 v[82:97], v[208:211], v[126:129], v[82:97]
	v_mfma_f32_32x32x16_bf16 v[66:81], v[212:215], v[126:129], v[66:81]
	ds_read_b128 v[210:213], v186 offset:49152
	ds_read_b128 v[232:235], v186 offset:57344
	s_waitcnt lgkmcnt(0)
	v_mfma_f32_32x32x16_bf16 v[82:97], v[210:213], v[122:125], v[82:97]
	v_mfma_f32_32x32x16_bf16 v[66:81], v[232:235], v[122:125], v[66:81]
	ds_read_b128 v[210:213], v188 offset:49152
	ds_read_b128 v[232:235], v188 offset:57344
	s_waitcnt lgkmcnt(0)
	v_mfma_f32_32x32x16_bf16 v[82:97], v[210:213], v[118:121], v[82:97]
	v_mfma_f32_32x32x16_bf16 v[66:81], v[232:235], v[118:121], v[66:81]
	ds_read_b128 v[212:215], v190 offset:49152
	ds_read_b128 v[232:235], v190 offset:57344
	s_waitcnt lgkmcnt(0)
	v_mfma_f32_32x32x16_bf16 v[82:97], v[212:215], v[114:117], v[82:97]
	v_mfma_f32_32x32x16_bf16 v[66:81], v[232:235], v[114:117], v[66:81]
	ds_read_b128 v[212:215], v192 offset:8192
	ds_read_b128 v[232:235], v192 offset:12288
	s_waitcnt lgkmcnt(0)
	v_mfma_f32_32x32x16_bf16 v[82:97], v[212:215], v[110:113], v[82:97]
	v_exp_f32_e32 v215, v163
	s_nop 0
	v_add_f32_e32 v146, v215, v146
	v_mfma_f32_32x32x16_bf16 v[66:81], v[232:235], v[110:113], v[66:81]
	ds_read_b128 v[232:235], v194 offset:8192
	ds_read_b128 v[236:239], v194 offset:12288
	v_add_f32_e32 v146, v156, v146
	v_add_f32_e32 v146, v157, v146
	s_waitcnt lgkmcnt(0)
	v_mfma_f32_32x32x16_bf16 v[82:97], v[232:235], v[106:109], v[82:97]
	v_mfma_f32_32x32x16_bf16 v[66:81], v[236:239], v[106:109], v[66:81]
	ds_read_b128 v[232:235], v196 offset:8192
	ds_read_b128 v[236:239], v196 offset:12288
	s_waitcnt lgkmcnt(0)
	v_mfma_f32_32x32x16_bf16 v[82:97], v[232:235], v[102:105], v[82:97]
	v_mfma_f32_32x32x16_bf16 v[66:81], v[236:239], v[102:105], v[66:81]
	ds_read_b128 v[232:235], v199 offset:8192
	ds_read_b128 v[236:239], v199 offset:12288
	s_waitcnt lgkmcnt(0)
	v_mfma_f32_32x32x16_bf16 v[82:97], v[232:235], v[98:101], v[82:97]
	v_exp_f32_e32 v232, v154
	v_exp_f32_e32 v233, v155
	v_exp_f32_e32 v234, v152
	v_exp_f32_e32 v235, v153
	v_add_f32_e32 v146, v232, v146
	v_add_f32_e32 v146, v233, v146
	v_add_f32_e32 v146, v234, v146
	v_mfma_f32_32x32x16_bf16 v[66:81], v[236:239], v[98:101], v[66:81]
	v_exp_f32_e32 v236, v150
	v_exp_f32_e32 v237, v151
	v_exp_f32_e32 v238, v148
	v_exp_f32_e32 v239, v149
	v_add_f32_e32 v146, v235, v146
	v_add_f32_e32 v146, v236, v146
	v_add_f32_e32 v146, v237, v146
	v_add_f32_e32 v146, v238, v146
	v_add_f32_e32 v146, v239, v146
	v_add_f32_e32 v146, v240, v146
	v_add_f32_e32 v162, v241, v146
	v_mov_b32_e32 v163, v162
	s_nop 1
	v_permlane32_swap_b32_e32 v162, v163
	v_cvt_pk_bf16_f32 v146, v229, v231
	v_cvt_pk_bf16_f32 v147, v227, v230
	v_cvt_pk_bf16_f32 v148, v226, v228
	v_cvt_pk_bf16_f32 v149, v224, v225
	v_cvt_pk_bf16_f32 v150, v221, v223
	v_cvt_pk_bf16_f32 v151, v220, v222
	v_cvt_pk_bf16_f32 v152, v217, v219
	v_cvt_pk_bf16_f32 v153, v216, v218
	v_cvt_pk_bf16_f32 v154, v164, v165
	v_cvt_pk_bf16_f32 v155, v197, v215
	v_cvt_pk_bf16_f32 v156, v156, v157
	v_cvt_pk_bf16_f32 v157, v232, v233
	v_cvt_pk_bf16_f32 v216, v234, v235
	v_cvt_pk_bf16_f32 v217, v236, v237
	v_cvt_pk_bf16_f32 v218, v238, v239
	v_cvt_pk_bf16_f32 v219, v240, v241
	s_nop 0
	v_permlane32_swap_b32_e32 v146, v148
	v_permlane32_swap_b32_e32 v147, v149
	v_permlane32_swap_b32_e32 v150, v152
	v_permlane32_swap_b32_e32 v151, v153
	v_permlane32_swap_b32_e32 v154, v156
	v_permlane32_swap_b32_e32 v155, v157
	v_permlane32_swap_b32_e32 v216, v218
	v_permlane32_swap_b32_e32 v217, v219
	s_lshl_b32 s24, s17, 14
	v_add_u32_e32 v197, s24, v200
	ds_read_b64_tr_b16 v[220:221], v197 offset:0
	ds_read_b64_tr_b16 v[222:223], v197 offset:0x800
	ds_read_b64_tr_b16 v[224:225], v197 offset:0x1000
	ds_read_b64_tr_b16 v[226:227], v197 offset:0x1800
	ds_read_b64_tr_b16 v[228:229], v197 offset:0x2000
	ds_read_b64_tr_b16 v[230:231], v197 offset:0x2800
	ds_read_b64_tr_b16 v[232:233], v197 offset:0x3000
	ds_read_b64_tr_b16 v[234:235], v197 offset:0x3800
	s_nop 0
	s_waitcnt lgkmcnt(6)
	v_mfma_f32_32x32x16_bf16 v[2:17], v[146:149], v[220:223], v[2:17]
	ds_read_b64_tr_b16 v[220:221], v197 offset:0x200
	ds_read_b64_tr_b16 v[222:223], v197 offset:0xa00
	v_max_f32_e32 v164, v83, v83
	v_max_f32_e32 v165, v82, v82
	v_max_f32_e32 v164, v165, v164
	v_max3_f32 v164, v164, v84, v85
	v_max3_f32 v164, v164, v86, v87
	s_waitcnt lgkmcnt(6)
	v_mfma_f32_32x32x16_bf16 v[2:17], v[150:153], v[224:227], v[2:17]
	ds_read_b64_tr_b16 v[224:225], v197 offset:0x1200
	ds_read_b64_tr_b16 v[226:227], v197 offset:0x1a00
	v_max3_f32 v164, v164, v88, v89
	v_max3_f32 v164, v164, v90, v91
	v_max3_f32 v164, v164, v92, v93
	v_max3_f32 v164, v164, v94, v95
	v_max3_f32 v164, v164, v96, v97
	s_waitcnt lgkmcnt(6)
	v_mfma_f32_32x32x16_bf16 v[2:17], v[154:157], v[228:231], v[2:17]
	ds_read_b64_tr_b16 v[228:229], v197 offset:0x2200
	ds_read_b64_tr_b16 v[230:231], v197 offset:0x2a00
	ds_read_b64_tr_b16 v[236:237], v197 offset:0x3200
	ds_read_b64_tr_b16 v[238:239], v197 offset:0x3a00
	s_waitcnt lgkmcnt(8)
	v_mfma_f32_32x32x16_bf16 v[2:17], v[216:219], v[232:235], v[2:17]
	s_waitcnt lgkmcnt(6)
	v_mfma_f32_32x32x16_bf16 v[50:65], v[146:149], v[220:223], v[50:65]
	v_max3_f32 v164, v164, v66, v67
	v_max3_f32 v164, v164, v68, v69
	v_max3_f32 v164, v164, v70, v71
	v_max3_f32 v164, v164, v72, v73
	v_max3_f32 v164, v164, v74, v75
	v_max3_f32 v164, v164, v76, v77
	v_max3_f32 v164, v164, v78, v79
	s_waitcnt lgkmcnt(4)
	v_mfma_f32_32x32x16_bf16 v[50:65], v[150:153], v[224:227], v[50:65]
	v_max3_f32 v164, v164, v80, v81
	v_mov_b32_e32 v165, v164
	s_nop 1
	v_permlane32_swap_b32_e32 v164, v165
	ds_read_b64_tr_b16 v[220:221], v197 offset:0x400
	v_max_f32_e32 v165, v165, v165
	v_max_f32_e32 v164, v164, v164
	s_waitcnt lgkmcnt(3)
	v_mfma_f32_32x32x16_bf16 v[50:65], v[154:157], v[228:231], v[50:65]
	ds_read_b64_tr_b16 v[222:223], v197 offset:0xc00
	v_max_f32_e32 v164, v164, v165
	v_max_f32_e32 v165, v202, v202
	ds_read_b64_tr_b16 v[224:225], v197 offset:0x1400
	v_max_f32_e32 v165, v165, v164
	ds_read_b64_tr_b16 v[226:227], v197 offset:0x1c00
	v_sub_f32_e32 v215, v164, v202
	s_waitcnt lgkmcnt(4)
	v_mfma_f32_32x32x16_bf16 v[50:65], v[216:219], v[236:239], v[50:65]
	v_sub_f32_e32 v164, v202, v165
	ds_read_b64_tr_b16 v[228:229], v197 offset:0x2400
	v_mul_f32_e32 v164, 0x3dd53b94, v164
	ds_read_b64_tr_b16 v[230:231], v197 offset:0x2c00
	v_exp_f32_e32 v164, v164
	ds_read_b64_tr_b16 v[232:233], v197 offset:0x3400
	v_cmp_ge_f32_e32 vcc, s77, v215
	ds_read_b64_tr_b16 v[234:235], v197 offset:0x3c00
	s_cmp_eq_u64 vcc, exec
	s_cselect_b64 s[4:5], -1, 0
	v_cndmask_b32_e64 v164, v164, 1.0, s[4:5]
	s_waitcnt lgkmcnt(6)
	v_mfma_f32_32x32x16_bf16 v[34:49], v[146:149], v[220:223], v[34:49]
	ds_read_b64_tr_b16 v[220:221], v197 offset:0x600
	ds_read_b64_tr_b16 v[222:223], v197 offset:0xe00
	s_waitcnt lgkmcnt(6)
	v_mfma_f32_32x32x16_bf16 v[34:49], v[150:153], v[224:227], v[34:49]
	ds_read_b64_tr_b16 v[224:225], v197 offset:0x1600
	ds_read_b64_tr_b16 v[226:227], v197 offset:0x1e00
	s_waitcnt lgkmcnt(6)
	v_mfma_f32_32x32x16_bf16 v[34:49], v[154:157], v[228:231], v[34:49]
	ds_read_b64_tr_b16 v[228:229], v197 offset:0x2600
	ds_read_b64_tr_b16 v[230:231], v197 offset:0x2e00
	ds_read_b64_tr_b16 v[236:237], v197 offset:0x3600
	ds_read_b64_tr_b16 v[238:239], v197 offset:0x3e00
	s_waitcnt lgkmcnt(8)
	v_mfma_f32_32x32x16_bf16 v[34:49], v[216:219], v[232:235], v[34:49]
	s_waitcnt lgkmcnt(6)
	v_mfma_f32_32x32x16_bf16 v[18:33], v[146:149], v[220:223], v[18:33]
	v_cmp_gt_f32_e32 vcc, 1.0, v164
	s_waitcnt lgkmcnt(4)
	v_mfma_f32_32x32x16_bf16 v[18:33], v[150:153], v[224:227], v[18:33]
	s_waitcnt lgkmcnt(2)
	v_mfma_f32_32x32x16_bf16 v[18:33], v[154:157], v[228:231], v[18:33]
	s_waitcnt lgkmcnt(0)
	v_mfma_f32_32x32x16_bf16 v[18:33], v[216:219], v[236:239], v[18:33]
	s_cbranch_vccz .Lmla_e_547
	s_and_saveexec_b64 s[0:1], s[2:3]
	ds_write_b32 v170, v164 offset:128
	s_or_b64 exec, exec, s[0:1]
	s_waitcnt lgkmcnt(0)
	ds_read_b128 v[146:149], v158 offset:224
	ds_read_b128 v[150:153], v158 offset:192
	ds_read_b128 v[154:157], v158 offset:160
	ds_read_b128 v[216:219], v158 offset:128
	s_waitcnt lgkmcnt(0)
	v_pk_mul_f32 v[16:17], v[16:17], v[148:149]
	v_pk_mul_f32 v[12:13], v[12:13], v[152:153]
	v_pk_mul_f32 v[8:9], v[8:9], v[156:157]
	v_pk_mul_f32 v[4:5], v[4:5], v[218:219]
	v_pk_mul_f32 v[14:15], v[14:15], v[146:147]
	v_pk_mul_f32 v[10:11], v[10:11], v[150:151]
	v_pk_mul_f32 v[6:7], v[6:7], v[154:155]
	v_pk_mul_f32 v[2:3], v[2:3], v[216:217]
	v_pk_mul_f32 v[64:65], v[64:65], v[148:149]
	v_pk_mul_f32 v[60:61], v[60:61], v[152:153]
	v_pk_mul_f32 v[56:57], v[56:57], v[156:157]
	v_pk_mul_f32 v[52:53], v[52:53], v[218:219]
	v_pk_mul_f32 v[62:63], v[62:63], v[146:147]
	v_pk_mul_f32 v[58:59], v[58:59], v[150:151]
	v_pk_mul_f32 v[54:55], v[54:55], v[154:155]
	v_pk_mul_f32 v[50:51], v[50:51], v[216:217]
	v_pk_mul_f32 v[48:49], v[48:49], v[148:149]
	v_pk_mul_f32 v[44:45], v[44:45], v[152:153]
	v_pk_mul_f32 v[40:41], v[40:41], v[156:157]
	v_pk_mul_f32 v[36:37], v[36:37], v[218:219]
	v_pk_mul_f32 v[46:47], v[46:47], v[146:147]
	v_pk_mul_f32 v[42:43], v[42:43], v[150:151]
	v_pk_mul_f32 v[38:39], v[38:39], v[154:155]
	v_pk_mul_f32 v[34:35], v[34:35], v[216:217]
	v_pk_mul_f32 v[32:33], v[32:33], v[148:149]
	v_pk_mul_f32 v[28:29], v[28:29], v[152:153]
	v_pk_mul_f32 v[24:25], v[24:25], v[156:157]
	v_pk_mul_f32 v[20:21], v[20:21], v[218:219]
	v_pk_mul_f32 v[30:31], v[30:31], v[146:147]
	v_pk_mul_f32 v[26:27], v[26:27], v[150:151]
	v_pk_mul_f32 v[22:23], v[22:23], v[154:155]
	v_pk_mul_f32 v[18:19], v[18:19], v[216:217]

.LBB0_553:
	v_cndmask_b32_e64 v202, v202, v165, s[4:5]
	v_mul_f32_e32 v146, 0xbdd53b94, v202
	v_fmamk_f32 v229, v82, 0x3dd53b94, v146
	v_fmamk_f32 v231, v83, 0x3dd53b94, v146
	v_fmamk_f32 v227, v84, 0x3dd53b94, v146
	v_fmamk_f32 v230, v85, 0x3dd53b94, v146
	v_fmamk_f32 v226, v86, 0x3dd53b94, v146
	v_fmamk_f32 v228, v87, 0x3dd53b94, v146
	v_fmamk_f32 v224, v88, 0x3dd53b94, v146
	v_fmamk_f32 v225, v89, 0x3dd53b94, v146
	v_fmamk_f32 v221, v90, 0x3dd53b94, v146
	v_fmamk_f32 v223, v91, 0x3dd53b94, v146
	v_fmamk_f32 v220, v92, 0x3dd53b94, v146
	v_fmamk_f32 v222, v93, 0x3dd53b94, v146
	v_fmamk_f32 v217, v94, 0x3dd53b94, v146
	v_fmamk_f32 v219, v95, 0x3dd53b94, v146
	v_fmamk_f32 v216, v96, 0x3dd53b94, v146
	v_fmamk_f32 v218, v97, 0x3dd53b94, v146
	s_add_u32 s88, s88, 0xf0000
	s_addc_u32 s87, s87, 0
	v_add_f32_e32 v82, v162, v163
	s_waitcnt vmcnt(0)
	s_add_u32 s20, s20, 0x80000
	v_fmac_f32_e32 v82, v201, v171
	v_add_f32_e32 v171, v232, v233
	s_addc_u32 s21, s21, 0
	s_add_i32 s19, s19, 2
	v_fmac_f32_e32 v171, v82, v164
	v_fma_f32 v164, v66, s34, v146
	v_fma_f32 v165, v67, s34, v146
	v_fma_f32 v162, v68, s34, v146
	v_fma_f32 v163, v69, s34, v146
	v_fma_f32 v156, v70, s34, v146
	v_fma_f32 v157, v71, s34, v146
	v_fma_f32 v154, v72, s34, v146
	v_fma_f32 v155, v73, s34, v146
	s_cmp_ge_u32 s19, s86
	s_mov_b32 s0, s22
	s_mov_b32 s22, s23
	v_mov_b32_e32 v201, v215
	s_waitcnt vmcnt(0)
	s_barrier
	s_cbranch_scc0 .LBB0_543
	v_fma_f32 v152, v74, s34, v146
	v_fma_f32 v153, v75, s34, v146
	v_fma_f32 v150, v76, s34, v146
	v_fma_f32 v151, v77, s34, v146
	v_fma_f32 v148, v78, s34, v146
	v_fma_f32 v149, v79, s34, v146
	v_fma_f32 v147, v81, s34, v146
	v_fma_f32 v146, v80, s34, v146
	v_exp_f32_e32 v229, v229
	v_exp_f32_e32 v231, v231
	v_exp_f32_e32 v227, v227
	v_exp_f32_e32 v230, v230
	v_exp_f32_e32 v226, v226
	v_exp_f32_e32 v228, v228
	v_exp_f32_e32 v224, v224
	v_exp_f32_e32 v225, v225
	v_exp_f32_e32 v221, v221
	v_exp_f32_e32 v223, v223
	v_exp_f32_e32 v220, v220
	v_exp_f32_e32 v222, v222
	v_exp_f32_e32 v217, v217
	v_exp_f32_e32 v219, v219
	v_exp_f32_e32 v216, v216
	v_exp_f32_e32 v218, v218
	s_setprio 0
